# P5a: odd workgroups run their two mlstm_pre items first, so VALU-bound and load-burst item types overlap across the chip instead of running in lockstep
# speedup vs baseline: 1.0023x; 1.0012x over previous
.LBB0_391:
	v_writelane_b32 v251, s84, 38
	s_nop 1
	v_writelane_b32 v251, s85, 39
	v_writelane_b32 v251, s62, 40
	s_nop 1
	v_writelane_b32 v251, s63, 41
	v_writelane_b32 v251, s86, 42
	s_cmp_lt_i32 s86, 6
	s_cselect_b64 s[2:3], -1, 0
	v_writelane_b32 v251, s87, 43
	s_add_u32 s87, s78, 0x16100000
	s_addc_u32 s4, s79, 0
	v_writelane_b32 v251, s4, 44
	s_add_u32 s4, s78, 0x18100000
	v_writelane_b32 v251, s4, 45
	s_addc_u32 s4, s79, 0
	s_add_u32 s84, s78, 0x19100000
	s_addc_u32 s85, s79, 0
	s_add_u32 s92, s78, 0x19200000
	v_writelane_b32 v251, s4, 46
	s_addc_u32 s93, s79, 0
	s_and_b64 s[0:1], s[2:3], s[0:1]
	v_cndmask_b32_e64 v0, 0, 1, s[0:1]
	v_writelane_b32 v251, s0, 47
	v_cmp_ne_u32_e64 s[2:3], 1, v0
	s_andn2_b64 vcc, exec, s[0:1]
	v_writelane_b32 v251, s1, 48
	v_writelane_b32 v251, s64, 49
	s_nop 1
	v_writelane_b32 v251, s65, 50
	v_writelane_b32 v251, s66, 51
	v_writelane_b32 v251, s67, 52
	v_writelane_b32 v251, s68, 53
	v_writelane_b32 v251, s69, 54
	v_writelane_b32 v251, s70, 55
	v_writelane_b32 v251, s71, 56
	v_writelane_b32 v251, s72, 57
	v_writelane_b32 v251, s73, 58
	v_writelane_b32 v251, s74, 59
	v_writelane_b32 v251, s75, 60
	v_writelane_b32 v251, s76, 61
	v_writelane_b32 v251, s77, 62
	v_writelane_b32 v251, s78, 63
	v_writelane_b32 v250, s79, 0
	s_cbranch_vccnz .LBB0_415
	v_writelane_b32 v250, s2, 1
	v_readlane_b32 s0, v251, 0
	s_cmpk_gt_i32 s0, 0x5ff
	v_writelane_b32 v250, s3, 2
	v_writelane_b32 v250, s16, 3
	s_cbranch_scc1 .LBB0_416
	v_cmp_eq_u32_e64 s[4:5], 63, v220
	v_lshrrev_b32_e32 v1, 2, v220
	v_and_b32_e32 v206, 12, v1
	v_writelane_b32 v250, s4, 4
	v_lshlrev_b32_e32 v1, 1, v221
	v_mov_b32_e32 v129, 0
	v_writelane_b32 v250, s5, 5
	v_cmp_gt_u32_e64 s[4:5], 2, v220
	v_and_b32_e32 v132, 0x7e, v1
	v_and_b32_e32 v1, 48, v220
	v_writelane_b32 v250, s4, 6
	v_lshlrev_b32_e32 v0, 4, v220
	v_add_u32_e32 v136, 0, v1
	v_writelane_b32 v250, s5, 7
	v_cmp_gt_u32_e64 s[4:5], 62, v220
	v_mov_b32_e32 v1, v129
	v_lshl_add_u64 v[138:139], s[78:79], 0, v[0:1]
	v_writelane_b32 v250, s4, 8
	v_add_u32_e32 v0, 0, v0
	v_add_u32_e32 v208, 0x10800, v0
	v_writelane_b32 v250, s5, 9
	v_cmp_gt_u32_e64 s[4:5], 4, v220
	v_lshlrev_b32_e32 v128, 5, v220
	v_mbcnt_lo_u32_b32 v0, -1, 0
	v_writelane_b32 v250, s4, 10
	v_mbcnt_hi_u32_b32 v210, -1, v0
	v_lshl_add_u64 v[130:131], s[6:7], 0, v[128:129]
	v_writelane_b32 v250, s5, 11
	v_cmp_gt_u32_e64 s[4:5], 60, v220
	v_lshlrev_b32_e32 v128, 2, v132
	v_readlane_b32 s89, v251, 0
	v_writelane_b32 v250, s4, 12
	v_and_b32_e32 v211, 64, v210
	v_lshlrev_b32_e32 v133, 1, v220
	v_writelane_b32 v250, s5, 13
	v_cmp_gt_u32_e64 s[4:5], 8, v220
	s_mov_b32 s1, 0
	v_cmp_eq_u32_e64 s[2:3], 0, v220
	v_writelane_b32 v250, s4, 14
	v_cmp_gt_u32_e64 s[22:23], 32, v220
	v_and_b32_e32 v137, 15, v221
	v_writelane_b32 v250, s5, 15
	v_cmp_gt_u32_e64 s[4:5], 56, v220
	v_lshl_add_u64 v[134:135], s[26:27], 0, v[128:129]
	v_add_u32_e32 v207, 0, v128
	v_writelane_b32 v250, s4, 16
	s_movk_i32 s7, 0x1000
	s_mov_b32 s33, 0x9000
	v_writelane_b32 v250, s5, 17
	v_cmp_gt_u32_e64 s[4:5], 16, v220
	s_movk_i32 s86, 0x2000
	s_movk_i32 s96, 0x3000
	v_writelane_b32 v250, s4, 18
	s_mov_b32 s10, 0x7f800000
	v_mov_b32_e32 v209, 0x3ecc95a3
	v_writelane_b32 v250, s5, 19
	v_cmp_gt_u32_e64 s[4:5], 48, v220
	s_mov_b32 s11, 0x3fb8aa3b
	s_mov_b32 s16, 0xc2ce8ed0
	v_writelane_b32 v250, s4, 20
	s_mov_b32 s17, 0x42b17218
	s_mov_b32 s20, 0x800000
	v_writelane_b32 v250, s5, 21
	s_add_i32 s5, s89, 0xfffffc00
	s_mov_b32 s32, 6
	s_bitcmp1_b32 s89, 0
	s_cselect_b32 s98, 0x400, 0
	s_add_i32 s89, s89, s98
	s_add_i32 s5, s5, s98
	s_mov_b32 s21, 0x3f317217
	v_add_u32_e32 v212, 64, v211
	v_xor_b32_e32 v213, 1, v210
	v_xor_b32_e32 v214, 2, v210
	v_xor_b32_e32 v215, 4, v210
	v_xor_b32_e32 v216, 8, v210
	v_xor_b32_e32 v217, 16, v210
	v_xor_b32_e32 v218, 32, v210
	v_mov_b32_e32 v219, 0x4800
	v_mov_b32_e32 v222, 0x7f800000
	v_mov_b32_e32 v140, 0x3f317218
	v_mov_b32_e32 v223, 0x41b17218
	s_mov_b32 s4, 0x3d800000
	s_mov_b32 s6, 0x3db504f3
	s_branch .LBB0_396

.LBB0_395:
	s_add_i32 s89, s89, s88
	s_add_i32 s5, s5, s88
	s_cmpk_gt_i32 s89, 0x5ff
	s_cselect_b32 s98, 0x600, 0
	s_sub_i32 s89, s89, s98
	s_sub_i32 s5, s5, s98
	s_add_i32 s32, s32, -1
	s_cmp_eq_u32 s32, 0
	s_cbranch_scc1 .LBB0_416
